# in-proj GEMM K-loop: per-block s_setprio toggles replaced by one static priority raise for waves 4-7
# speedup vs baseline: 1.0020x; 1.0020x over previous
; template <class Epi, class Sched>
; __device__ __forceinline__ void gemm_phase(const int TID, LAS unsigned char* lds, const int lda, const int ldb, const Sched& S, const Epi& E) {
;     ...
;     for (;;) {
;         const bool has_next = S.next(ui + 1, nxt);
;         const char* nA = has_next ? nxt.a : cA; const char* nB = has_next ? nxt.b : cB;
;         const int nt = cur.nt;
;         for (int t = 0; t < nt; t += 2) {
.LBB0_1228:
	s_cmpk_gt_u32 s53, 0xff
	s_cbranch_scc0 .Lk1_noprio
	s_setprio 1

; #define PG8_STAGE(bufoff, gbase, voff) do { _Pragma("unroll") for (int _i = 0; _i < 2; ++_i) \
;         __builtin_amdgcn_global_load_lds((const unsigned*)((const char*)(gbase) + (voff)[_i]), (LAS unsigned*)(lds + (bufoff) + ldsw + _i * 8192), 16, 0, 0); } while (0)
; #define PG8_LDA(dst, b, h) do { _Pragma("unroll") for (int m = 0; m < 4; ++m) _Pragma("unroll") for (int k = 0; k < 2; ++k) dst[m][k] = *(const LAS bf16x8*)(lds + PG8_SA(b, h) + aoff + m * 2048 + k * 1024); } while (0)
; #define PG8_LDB(dst, b, h) do { _Pragma("unroll") for (int n = 0; n < 2; ++n) _Pragma("unroll") for (int k = 0; k < 2; ++k) dst[n][k] = *(const LAS bf16x8*)(lds + PG8_SB(b, h) + boff + n * 2048 + k * 1024); } while (0)
; #define PG8_MMA(ai, bj, At, Bt) do { __builtin_amdgcn_s_setprio(1); _Pragma("unroll") for (int m = 0; m < 4; ++m) _Pragma("unroll") for (int n = 0; n < 2; ++n) _Pragma("unroll") for (int k = 0; k < 2; ++k) \
;         acc[ai][bj][m][n] = __builtin_amdgcn_mfma_f32_16x16x32_bf16(Bt[n][k], At[m][k], acc[ai][bj][m][n], 0, 0, 0); __builtin_amdgcn_s_setprio(0); } while (0)
; #define PG8_WAIT_V(n) asm volatile("s_waitcnt vmcnt(" #n ")" ::: "memory")
; #define PG8_WAIT_L(n) asm volatile("s_waitcnt lgkmcnt(" #n ")" ::: "memory")
; #define PG8_BAR __builtin_amdgcn_s_barrier()
; template <class Epi, class Sched>
; __device__ __forceinline__ void gemm_phase(const int TID, LAS unsigned char* lds, const int lda, const int ldb, const Sched& S, const Epi& E) {
;     ...
;             const char* a1 = cA + (size_t)(t + 1) * kstep;
;             const char* a2 = last ? nA : cA + (size_t)(t + 2) * kstep; const char* b2 = last ? nB : cB + (size_t)(t + 2) * kstep;
;             const char* a3 = a2 + kstep; const char* b3 = b2 + kstep;
;             PG8_LDB(B0, 0, 0); PG8_SCHED; PG8_LDA(At, 0, 0); PG8_STAGE(PG8_SA(1, 1), a1 + hA, voffA);
;             PG8_WAIT_L(8); PG8_BAR; PG8_WAIT_L(0); PG8_MMA(0, 0, At, B0); PG8_BAR; PG8_SCHED;
;             PG8_LDB(B1, 0, 1); PG8_STAGE(PG8_SB(0, 0), b2, voffB);
;             PG8_BAR; PG8_WAIT_L(0); PG8_MMA(0, 1, At, B1); PG8_BAR;
;             PG8_LDA(At, 0, 1); PG8_STAGE(PG8_SA(0, 0), a2, voffA);
;             PG8_BAR; PG8_WAIT_L(0); PG8_MMA(1, 0, At, B0); PG8_BAR; PG8_SCHED;
;             PG8_STAGE(PG8_SB(0, 1), b2 + hB, voffB);
;             PG8_WAIT_V(6); PG8_BAR; PG8_MMA(1, 1, At, B1); PG8_BAR;
.Lk1_body:
	s_add_u32 s8, s46, 0xfff80080
	s_addc_u32 s9, s47, -1
	s_add_i32 s10, 0, 0x10000
	s_cmp_eq_u32 s29, 28
	s_cselect_b32 s51, s43, s9
	s_cselect_b32 s50, s42, s8
	s_cselect_b32 s49, s45, s24
	s_cselect_b32 s48, s44, s3
	v_lshl_add_u64 v[154:155], s[46:47], 0, v[148:149]
	s_add_i32 m0, s57, 0xc000
	ds_read_b128 v[170:173], v157
	ds_read_b128 v[174:177], v157 offset:1024
	ds_read_b128 v[178:181], v157 offset:2048
	ds_read_b128 v[196:199], v157 offset:3072
	ds_read_b128 v[200:203], v157 offset:4096
	ds_read_b128 v[204:207], v157 offset:5120
	ds_read_b128 v[208:211], v157 offset:6144
	ds_read_b128 v[212:215], v157 offset:7168
	global_load_lds_dwordx4 v[154:155], off
	v_lshl_add_u64 v[154:155], s[46:47], 0, v[146:147]
	s_add_i32 m0, s57, 0xe000
	s_nop 0
	global_load_lds_dwordx4 v[154:155], off
	s_waitcnt lgkmcnt(8)
	s_barrier
	s_waitcnt lgkmcnt(0)
	s_waitcnt lgkmcnt(0)
	v_mfma_f32_16x16x32_bf16 v[130:133], v[150:153], v[170:173], v[130:133]
	v_mfma_f32_16x16x32_bf16 v[126:129], v[162:165], v[170:173], v[126:129]
	v_mfma_f32_16x16x32_bf16 v[114:117], v[150:153], v[178:181], v[114:117]
	v_mfma_f32_16x16x32_bf16 v[110:113], v[162:165], v[178:181], v[110:113]
	v_mfma_f32_16x16x32_bf16 v[98:101], v[150:153], v[200:203], v[98:101]
	v_mfma_f32_16x16x32_bf16 v[94:97], v[162:165], v[200:203], v[94:97]
	v_mfma_f32_16x16x32_bf16 v[82:85], v[150:153], v[208:211], v[82:85]
	v_mfma_f32_16x16x32_bf16 v[78:81], v[162:165], v[208:211], v[78:81]
	v_mfma_f32_16x16x32_bf16 v[130:133], v[158:161], v[174:177], v[130:133]
	v_mfma_f32_16x16x32_bf16 v[126:129], v[166:169], v[174:177], v[126:129]
	v_mfma_f32_16x16x32_bf16 v[114:117], v[158:161], v[196:199], v[114:117]
	v_mfma_f32_16x16x32_bf16 v[110:113], v[166:169], v[196:199], v[110:113]
	v_mfma_f32_16x16x32_bf16 v[98:101], v[158:161], v[204:207], v[98:101]
	v_mfma_f32_16x16x32_bf16 v[94:97], v[166:169], v[204:207], v[94:97]
	v_mfma_f32_16x16x32_bf16 v[82:85], v[158:161], v[212:215], v[82:85]
	v_mfma_f32_16x16x32_bf16 v[78:81], v[166:169], v[212:215], v[78:81]
	s_barrier
	s_add_i32 s8, 0, 0x14000
	v_add_u32_e32 v154, s8, v13
	s_add_i32 s9, s10, s56
	ds_read_b128 v[216:219], v154
	ds_read_b128 v[220:223], v154 offset:1024
	ds_read_b128 v[236:239], v154 offset:2048
	ds_read_b128 v[240:243], v154 offset:3072
	v_lshl_add_u64 v[154:155], s[48:49], 0, v[136:137]
	s_mov_b32 m0, s9
	v_lshl_add_u64 v[186:187], s[48:49], 0, v[140:141]
	global_load_lds_dwordx4 v[154:155], off
	s_add_i32 m0, s9, 0x2000
	s_nop 0
	global_load_lds_dwordx4 v[186:187], off
	s_barrier
	s_waitcnt lgkmcnt(0)
	s_waitcnt lgkmcnt(0)
	v_mfma_f32_16x16x32_bf16 v[122:125], v[216:219], v[170:173], v[122:125]
	v_mfma_f32_16x16x32_bf16 v[118:121], v[236:239], v[170:173], v[118:121]
	v_mfma_f32_16x16x32_bf16 v[106:109], v[216:219], v[178:181], v[106:109]
	v_mfma_f32_16x16x32_bf16 v[102:105], v[236:239], v[178:181], v[102:105]
	v_mfma_f32_16x16x32_bf16 v[90:93], v[216:219], v[200:203], v[90:93]
	v_mfma_f32_16x16x32_bf16 v[86:89], v[236:239], v[200:203], v[86:89]
	v_mfma_f32_16x16x32_bf16 v[74:77], v[216:219], v[208:211], v[74:77]
	v_mfma_f32_16x16x32_bf16 v[70:73], v[236:239], v[208:211], v[70:73]
	v_mfma_f32_16x16x32_bf16 v[122:125], v[220:223], v[174:177], v[122:125]
	v_mfma_f32_16x16x32_bf16 v[118:121], v[240:243], v[174:177], v[118:121]
	v_mfma_f32_16x16x32_bf16 v[106:109], v[220:223], v[196:199], v[106:109]
	v_mfma_f32_16x16x32_bf16 v[102:105], v[240:243], v[196:199], v[102:105]
	v_mfma_f32_16x16x32_bf16 v[90:93], v[220:223], v[204:207], v[90:93]
	v_mfma_f32_16x16x32_bf16 v[86:89], v[240:243], v[204:207], v[86:89]
	v_mfma_f32_16x16x32_bf16 v[74:77], v[220:223], v[212:215], v[74:77]
	v_mfma_f32_16x16x32_bf16 v[70:73], v[240:243], v[212:215], v[70:73]
	s_mov_b32 m0, s57
	v_lshl_add_u64 v[188:189], s[50:51], 0, v[134:135]
	s_barrier
	ds_read_b128 v[170:173], v157 offset:16384
	ds_read_b128 v[174:177], v157 offset:17408
	ds_read_b128 v[178:181], v157 offset:18432
	ds_read_b128 v[196:199], v157 offset:19456
	ds_read_b128 v[200:203], v157 offset:20480
	ds_read_b128 v[204:207], v157 offset:21504
	ds_read_b128 v[208:211], v157 offset:22528
	ds_read_b128 v[212:215], v157 offset:23552
	global_load_lds_dwordx4 v[188:189], off
	v_lshl_add_u64 v[244:245], s[50:51], 0, v[138:139]
	s_mov_b32 m0, s58
	s_nop 0
	global_load_lds_dwordx4 v[244:245], off
	s_barrier
	s_waitcnt lgkmcnt(0)
	s_waitcnt lgkmcnt(0)
	v_mfma_f32_16x16x32_bf16 v[66:69], v[150:153], v[170:173], v[66:69]
	v_mfma_f32_16x16x32_bf16 v[62:65], v[162:165], v[170:173], v[62:65]
	v_mfma_f32_16x16x32_bf16 v[50:53], v[150:153], v[178:181], v[50:53]
	v_mfma_f32_16x16x32_bf16 v[46:49], v[162:165], v[178:181], v[46:49]
	v_mfma_f32_16x16x32_bf16 v[34:37], v[150:153], v[200:203], v[34:37]
	v_mfma_f32_16x16x32_bf16 v[30:33], v[162:165], v[200:203], v[30:33]
	v_mfma_f32_16x16x32_bf16 v[18:21], v[150:153], v[208:211], v[18:21]
	v_mfma_f32_16x16x32_bf16 v[8:11], v[162:165], v[208:211], v[8:11]
	v_mfma_f32_16x16x32_bf16 v[66:69], v[158:161], v[174:177], v[66:69]
	v_mfma_f32_16x16x32_bf16 v[62:65], v[166:169], v[174:177], v[62:65]
	v_mfma_f32_16x16x32_bf16 v[50:53], v[158:161], v[196:199], v[50:53]
	v_mfma_f32_16x16x32_bf16 v[46:49], v[166:169], v[196:199], v[46:49]
	v_mfma_f32_16x16x32_bf16 v[34:37], v[158:161], v[204:207], v[34:37]
	v_mfma_f32_16x16x32_bf16 v[30:33], v[166:169], v[204:207], v[30:33]
	v_mfma_f32_16x16x32_bf16 v[18:21], v[158:161], v[212:215], v[18:21]
	v_mfma_f32_16x16x32_bf16 v[8:11], v[166:169], v[212:215], v[8:11]
	s_barrier
; #define PG8_STAGE(bufoff, gbase, voff) do { _Pragma("unroll") for (int _i = 0; _i < 2; ++_i) \
;         __builtin_amdgcn_global_load_lds((const unsigned*)((const char*)(gbase) + (voff)[_i]), (LAS unsigned*)(lds + (bufoff) + ldsw + _i * 8192), 16, 0, 0); } while (0)
; #define PG8_LDA(dst, b, h) do { _Pragma("unroll") for (int m = 0; m < 4; ++m) _Pragma("unroll") for (int k = 0; k < 2; ++k) dst[m][k] = *(const LAS bf16x8*)(lds + PG8_SA(b, h) + aoff + m * 2048 + k * 1024); } while (0)
; #define PG8_LDB(dst, b, h) do { _Pragma("unroll") for (int n = 0; n < 2; ++n) _Pragma("unroll") for (int k = 0; k < 2; ++k) dst[n][k] = *(const LAS bf16x8*)(lds + PG8_SB(b, h) + boff + n * 2048 + k * 1024); } while (0)
; #define PG8_MMA(ai, bj, At, Bt) do { __builtin_amdgcn_s_setprio(1); _Pragma("unroll") for (int m = 0; m < 4; ++m) _Pragma("unroll") for (int n = 0; n < 2; ++n) _Pragma("unroll") for (int k = 0; k < 2; ++k) \
;         acc[ai][bj][m][n] = __builtin_amdgcn_mfma_f32_16x16x32_bf16(Bt[n][k], At[m][k], acc[ai][bj][m][n], 0, 0, 0); __builtin_amdgcn_s_setprio(0); } while (0)
; #define PG8_WAIT_V(n) asm volatile("s_waitcnt vmcnt(" #n ")" ::: "memory")
; #define PG8_WAIT_L(n) asm volatile("s_waitcnt lgkmcnt(" #n ")" ::: "memory")
; #define PG8_BAR __builtin_amdgcn_s_barrier()
; #define PG8_SCHED __builtin_amdgcn_sched_barrier(0)
; template <class Epi, class Sched>
; __device__ __forceinline__ void gemm_phase(const int TID, LAS unsigned char* lds, const int lda, const int ldb, const Sched& S, const Epi& E) {
;     ...
;             PG8_WAIT_V(6); PG8_BAR; PG8_MMA(1, 1, At, B1); PG8_BAR;
;             PG8_LDB(B0, 1, 0); PG8_SCHED; PG8_LDA(At, 1, 0); PG8_STAGE(PG8_SA(0, 1), a2 + hA, voffA);
;             PG8_WAIT_L(8); PG8_BAR; PG8_WAIT_L(0); PG8_MMA(0, 0, At, B0); PG8_BAR; PG8_SCHED;
;             PG8_LDB(B1, 1, 1); PG8_STAGE(PG8_SB(1, 0), b3, voffB);
;             PG8_BAR; PG8_WAIT_L(0); PG8_MMA(0, 1, At, B1); PG8_BAR;
;             PG8_LDA(At, 1, 1); PG8_STAGE(PG8_SA(1, 0), a3, voffA);
;             PG8_BAR; PG8_WAIT_L(0); PG8_MMA(1, 0, At, B0); PG8_BAR; PG8_SCHED;
	s_add_u32 s66, s48, 0x80000
	s_addc_u32 s67, s49, 0
	s_add_i32 s8, s8, s56
	v_lshl_add_u64 v[150:151], s[66:67], 0, v[136:137]
	s_mov_b32 m0, s8
	s_nop 0
	global_load_lds_dwordx4 v[150:151], off
	v_lshl_add_u64 v[150:151], s[66:67], 0, v[140:141]
	s_add_i32 m0, s8, 0x2000
	s_nop 0
	global_load_lds_dwordx4 v[150:151], off
	s_waitcnt vmcnt(6)
	s_barrier
	v_add_u32_e32 v166, 0x18000, v13
	v_mfma_f32_16x16x32_bf16 v[58:61], v[216:219], v[170:173], v[58:61]
	v_mfma_f32_16x16x32_bf16 v[54:57], v[236:239], v[170:173], v[54:57]
	v_mfma_f32_16x16x32_bf16 v[42:45], v[216:219], v[178:181], v[42:45]
	v_mfma_f32_16x16x32_bf16 v[38:41], v[236:239], v[178:181], v[38:41]
	ds_read_b128 v[150:153], v166
	v_mfma_f32_16x16x32_bf16 v[26:29], v[216:219], v[200:203], v[26:29]
	v_mfma_f32_16x16x32_bf16 v[22:25], v[236:239], v[200:203], v[22:25]
	ds_read_b128 v[158:161], v166 offset:1024
	v_mfma_f32_16x16x32_bf16 v[4:7], v[216:219], v[208:211], v[4:7]
	v_mfma_f32_16x16x32_bf16 v[0:3], v[236:239], v[208:211], v[0:3]
	ds_read_b128 v[162:165], v166 offset:2048
	v_mfma_f32_16x16x32_bf16 v[58:61], v[220:223], v[174:177], v[58:61]
	v_mfma_f32_16x16x32_bf16 v[54:57], v[240:243], v[174:177], v[54:57]
	ds_read_b128 v[166:169], v166 offset:3072
	v_mfma_f32_16x16x32_bf16 v[42:45], v[220:223], v[196:199], v[42:45]
	v_mfma_f32_16x16x32_bf16 v[38:41], v[240:243], v[196:199], v[38:41]
	v_mfma_f32_16x16x32_bf16 v[26:29], v[220:223], v[204:207], v[26:29]
	v_mfma_f32_16x16x32_bf16 v[22:25], v[240:243], v[204:207], v[22:25]
	v_mfma_f32_16x16x32_bf16 v[4:7], v[220:223], v[212:215], v[4:7]
	v_mfma_f32_16x16x32_bf16 v[0:3], v[240:243], v[212:215], v[0:3]
	s_add_i32 s8, 0, 0x18000
	s_barrier
	s_add_u32 s50, s50, 0x80000
	s_addc_u32 s51, s51, 0
	s_mov_b32 m0, s59
	v_lshl_add_u64 v[216:217], s[50:51], 0, v[134:135]
	ds_read_b128 v[170:173], v157 offset:32768
	ds_read_b128 v[174:177], v157 offset:33792
	ds_read_b128 v[178:181], v157 offset:34816
	ds_read_b128 v[196:199], v157 offset:35840
	ds_read_b128 v[200:203], v157 offset:36864
	ds_read_b128 v[204:207], v157 offset:37888
	ds_read_b128 v[208:211], v157 offset:38912
	ds_read_b128 v[212:215], v157 offset:39936
	global_load_lds_dwordx4 v[216:217], off
	v_lshl_add_u64 v[216:217], s[50:51], 0, v[138:139]
	s_mov_b32 m0, s60
	s_nop 0
	global_load_lds_dwordx4 v[216:217], off
	s_waitcnt lgkmcnt(8)
	s_barrier
	s_waitcnt lgkmcnt(0)
	s_waitcnt lgkmcnt(0)
	v_mfma_f32_16x16x32_bf16 v[130:133], v[150:153], v[170:173], v[130:133]
	v_mfma_f32_16x16x32_bf16 v[126:129], v[162:165], v[170:173], v[126:129]
	v_mfma_f32_16x16x32_bf16 v[114:117], v[150:153], v[178:181], v[114:117]
	v_mfma_f32_16x16x32_bf16 v[110:113], v[162:165], v[178:181], v[110:113]
	v_mfma_f32_16x16x32_bf16 v[98:101], v[150:153], v[200:203], v[98:101]
	v_mfma_f32_16x16x32_bf16 v[94:97], v[162:165], v[200:203], v[94:97]
	v_mfma_f32_16x16x32_bf16 v[82:85], v[150:153], v[208:211], v[82:85]
	v_mfma_f32_16x16x32_bf16 v[78:81], v[162:165], v[208:211], v[78:81]
	v_mfma_f32_16x16x32_bf16 v[130:133], v[158:161], v[174:177], v[130:133]
	v_mfma_f32_16x16x32_bf16 v[126:129], v[166:169], v[174:177], v[126:129]
	v_mfma_f32_16x16x32_bf16 v[114:117], v[158:161], v[196:199], v[114:117]
	v_mfma_f32_16x16x32_bf16 v[110:113], v[166:169], v[196:199], v[110:113]
	v_mfma_f32_16x16x32_bf16 v[98:101], v[158:161], v[204:207], v[98:101]
	v_mfma_f32_16x16x32_bf16 v[94:97], v[166:169], v[204:207], v[94:97]
	v_mfma_f32_16x16x32_bf16 v[82:85], v[158:161], v[212:215], v[82:85]
	v_mfma_f32_16x16x32_bf16 v[78:81], v[166:169], v[212:215], v[78:81]
	s_barrier
	s_add_i32 s9, 0, 0x1c000
	s_add_i32 s8, s8, s56
	v_add_u32_e32 v182, s9, v13
	v_lshl_add_u64 v[154:155], v[154:155], 0, s[36:37]
	s_mov_b32 m0, s8
	ds_read_b128 v[216:219], v182
	ds_read_b128 v[220:223], v182 offset:1024
	ds_read_b128 v[236:239], v182 offset:2048
	ds_read_b128 v[240:243], v182 offset:3072
	global_load_lds_dwordx4 v[154:155], off
	v_lshl_add_u64 v[154:155], v[186:187], 0, s[36:37]
	s_add_i32 m0, s8, 0x2000
	s_nop 0
	global_load_lds_dwordx4 v[154:155], off
	s_barrier
	s_waitcnt lgkmcnt(0)
	s_waitcnt lgkmcnt(0)
	v_mfma_f32_16x16x32_bf16 v[122:125], v[216:219], v[170:173], v[122:125]
	v_mfma_f32_16x16x32_bf16 v[118:121], v[236:239], v[170:173], v[118:121]
	v_mfma_f32_16x16x32_bf16 v[106:109], v[216:219], v[178:181], v[106:109]
	v_mfma_f32_16x16x32_bf16 v[102:105], v[236:239], v[178:181], v[102:105]
	v_mfma_f32_16x16x32_bf16 v[90:93], v[216:219], v[200:203], v[90:93]
	v_mfma_f32_16x16x32_bf16 v[86:89], v[236:239], v[200:203], v[86:89]
	v_mfma_f32_16x16x32_bf16 v[74:77], v[216:219], v[208:211], v[74:77]
	v_mfma_f32_16x16x32_bf16 v[70:73], v[236:239], v[208:211], v[70:73]
	v_mfma_f32_16x16x32_bf16 v[122:125], v[220:223], v[174:177], v[122:125]
	v_mfma_f32_16x16x32_bf16 v[118:121], v[240:243], v[174:177], v[118:121]
	v_mfma_f32_16x16x32_bf16 v[106:109], v[220:223], v[196:199], v[106:109]
	v_mfma_f32_16x16x32_bf16 v[102:105], v[240:243], v[196:199], v[102:105]
	v_mfma_f32_16x16x32_bf16 v[90:93], v[220:223], v[204:207], v[90:93]
	v_mfma_f32_16x16x32_bf16 v[86:89], v[240:243], v[204:207], v[86:89]
	v_mfma_f32_16x16x32_bf16 v[74:77], v[220:223], v[212:215], v[74:77]
	v_mfma_f32_16x16x32_bf16 v[70:73], v[240:243], v[212:215], v[70:73]
	s_mov_b32 m0, s62
	v_lshl_add_u64 v[154:155], v[188:189], 0, s[36:37]
	s_barrier
; #define PG8_STAGE(bufoff, gbase, voff) do { _Pragma("unroll") for (int _i = 0; _i < 2; ++_i) \
;         __builtin_amdgcn_global_load_lds((const unsigned*)((const char*)(gbase) + (voff)[_i]), (LAS unsigned*)(lds + (bufoff) + ldsw + _i * 8192), 16, 0, 0); } while (0)
; #define PG8_LDA(dst, b, h) do { _Pragma("unroll") for (int m = 0; m < 4; ++m) _Pragma("unroll") for (int k = 0; k < 2; ++k) dst[m][k] = *(const LAS bf16x8*)(lds + PG8_SA(b, h) + aoff + m * 2048 + k * 1024); } while (0)
; #define PG8_MMA(ai, bj, At, Bt) do { __builtin_amdgcn_s_setprio(1); _Pragma("unroll") for (int m = 0; m < 4; ++m) _Pragma("unroll") for (int n = 0; n < 2; ++n) _Pragma("unroll") for (int k = 0; k < 2; ++k) \
;         acc[ai][bj][m][n] = __builtin_amdgcn_mfma_f32_16x16x32_bf16(Bt[n][k], At[m][k], acc[ai][bj][m][n], 0, 0, 0); __builtin_amdgcn_s_setprio(0); } while (0)
; #define PG8_WAIT_V(n) asm volatile("s_waitcnt vmcnt(" #n ")" ::: "memory")
; #define PG8_WAIT_L(n) asm volatile("s_waitcnt lgkmcnt(" #n ")" ::: "memory")
; #define PG8_BAR __builtin_amdgcn_s_barrier()
; #define PG8_SCHED __builtin_amdgcn_sched_barrier(0)
; template <class Epi, class Sched>
; __device__ __forceinline__ void gemm_phase(const int TID, LAS unsigned char* lds, const int lda, const int ldb, const Sched& S, const Epi& E) {
;     ...
;             PG8_LDA(At, 1, 1); PG8_STAGE(PG8_SA(1, 0), a3, voffA);
;             PG8_BAR; PG8_WAIT_L(0); PG8_MMA(1, 0, At, B0); PG8_BAR; PG8_SCHED;
;             PG8_STAGE(PG8_SB(1, 1), b3 + hB, voffB);
;             PG8_WAIT_V(6); PG8_BAR; PG8_MMA(1, 1, At, B1); PG8_BAR;
	ds_read_b128 v[170:173], v157 offset:49152
	ds_read_b128 v[174:177], v157 offset:50176
	ds_read_b128 v[178:181], v157 offset:51200
	ds_read_b128 v[196:199], v157 offset:52224
	ds_read_b128 v[200:203], v157 offset:53248
	ds_read_b128 v[204:207], v157 offset:54272
	ds_read_b128 v[208:211], v157 offset:55296
	ds_read_b128 v[212:215], v157 offset:56320
	global_load_lds_dwordx4 v[154:155], off
	v_lshl_add_u64 v[154:155], v[244:245], 0, s[36:37]
	s_mov_b32 m0, s63
	s_nop 0
	global_load_lds_dwordx4 v[154:155], off
	s_barrier
	s_waitcnt lgkmcnt(0)
	s_waitcnt lgkmcnt(0)
	v_mfma_f32_16x16x32_bf16 v[66:69], v[150:153], v[170:173], v[66:69]
	v_mfma_f32_16x16x32_bf16 v[62:65], v[162:165], v[170:173], v[62:65]
	v_mfma_f32_16x16x32_bf16 v[50:53], v[150:153], v[178:181], v[50:53]
	v_mfma_f32_16x16x32_bf16 v[46:49], v[162:165], v[178:181], v[46:49]
	v_mfma_f32_16x16x32_bf16 v[34:37], v[150:153], v[200:203], v[34:37]
	v_mfma_f32_16x16x32_bf16 v[30:33], v[162:165], v[200:203], v[30:33]
	v_mfma_f32_16x16x32_bf16 v[18:21], v[150:153], v[208:211], v[18:21]
	v_mfma_f32_16x16x32_bf16 v[8:11], v[162:165], v[208:211], v[8:11]
	v_mfma_f32_16x16x32_bf16 v[66:69], v[158:161], v[174:177], v[66:69]
	v_mfma_f32_16x16x32_bf16 v[62:65], v[166:169], v[174:177], v[62:65]
	v_mfma_f32_16x16x32_bf16 v[50:53], v[158:161], v[196:199], v[50:53]
	v_mfma_f32_16x16x32_bf16 v[46:49], v[166:169], v[196:199], v[46:49]
	v_mfma_f32_16x16x32_bf16 v[34:37], v[158:161], v[204:207], v[34:37]
	v_mfma_f32_16x16x32_bf16 v[30:33], v[166:169], v[204:207], v[30:33]
	v_mfma_f32_16x16x32_bf16 v[18:21], v[158:161], v[212:215], v[18:21]
	v_mfma_f32_16x16x32_bf16 v[8:11], v[166:169], v[212:215], v[8:11]
	s_barrier
	s_add_u32 s48, s48, 0x80080
	s_addc_u32 s49, s49, 0
	s_add_i32 s8, s9, s56
	v_lshl_add_u64 v[150:151], s[48:49], 0, v[136:137]
	s_mov_b32 m0, s8
	s_nop 0
	global_load_lds_dwordx4 v[150:151], off
	v_lshl_add_u64 v[150:151], s[48:49], 0, v[140:141]
	s_add_i32 m0, s8, 0x2000
	s_nop 0
	global_load_lds_dwordx4 v[150:151], off
	s_waitcnt vmcnt(6)
	s_barrier
	v_add_u32_e32 v154, 0x10000, v13
	v_mfma_f32_16x16x32_bf16 v[58:61], v[216:219], v[170:173], v[58:61]
	v_mfma_f32_16x16x32_bf16 v[54:57], v[236:239], v[170:173], v[54:57]
	v_mfma_f32_16x16x32_bf16 v[42:45], v[216:219], v[178:181], v[42:45]
	v_mfma_f32_16x16x32_bf16 v[38:41], v[236:239], v[178:181], v[38:41]
	ds_read_b128 v[150:153], v154
	v_mfma_f32_16x16x32_bf16 v[26:29], v[216:219], v[200:203], v[26:29]
	v_mfma_f32_16x16x32_bf16 v[22:25], v[236:239], v[200:203], v[22:25]
	ds_read_b128 v[158:161], v154 offset:1024
	v_mfma_f32_16x16x32_bf16 v[4:7], v[216:219], v[208:211], v[4:7]
	v_mfma_f32_16x16x32_bf16 v[0:3], v[236:239], v[208:211], v[0:3]
	ds_read_b128 v[162:165], v154 offset:2048
	v_mfma_f32_16x16x32_bf16 v[58:61], v[220:223], v[174:177], v[58:61]
	v_mfma_f32_16x16x32_bf16 v[54:57], v[240:243], v[174:177], v[54:57]
	ds_read_b128 v[166:169], v154 offset:3072
	v_mfma_f32_16x16x32_bf16 v[42:45], v[220:223], v[196:199], v[42:45]
	v_mfma_f32_16x16x32_bf16 v[38:41], v[240:243], v[196:199], v[38:41]
	v_mfma_f32_16x16x32_bf16 v[26:29], v[220:223], v[204:207], v[26:29]
	v_mfma_f32_16x16x32_bf16 v[22:25], v[240:243], v[204:207], v[22:25]
	v_mfma_f32_16x16x32_bf16 v[4:7], v[220:223], v[212:215], v[4:7]
	v_mfma_f32_16x16x32_bf16 v[0:3], v[240:243], v[212:215], v[0:3]
	s_add_i32 s29, s29, 2
	s_add_u32 s3, s3, 0x100
	s_addc_u32 s24, s24, 0
	s_add_u32 s46, s46, 0x100
	s_addc_u32 s47, s47, 0
	s_cmp_gt_u32 s29, 29
	s_barrier
	s_cbranch_scc0 .Lk1_body
	s_setprio 0
	s_waitcnt lgkmcnt(0)
	s_lshl_b32 s3, s40, 8
	s_sub_i32 s8, s65, 18
	s_add_i32 s3, s3, s61
	s_lshl_b32 s24, s65, 8
	s_cmp_gt_u32 s8, 23
	v_or_b32_e32 v158, s3, v12
	s_mov_b64 s[40:41], -1
	s_cbranch_scc0 .LBB0_1295
	s_cmp_gt_i32 s65, 1
	s_cselect_b64 s[46:47], -1, 0
	v_mad_i64_i32 v[150:151], s[40:41], v158, s4, 0
	v_or_b32_e32 v182, s24, v156
	s_mov_b64 s[40:41], -1
	s_and_b64 vcc, exec, s[46:47]
	v_lshl_add_u64 v[150:151], s[0:1], 0, v[150:151]
	s_cbranch_vccz .LBB0_1232
	v_lshl_add_u64 v[152:153], v[182:183], 1, v[150:151]
	s_mov_b64 s[40:41], 0
